# conv_even taps: 12 tap loads issued up front per item (on top of mlp1 epilogue hoist+coalesced stores, attention QK/PV LDS prefetch, prep gate aux hoist, G2 scan batching)
# speedup vs baseline: 1.0183x; 1.0002x over previous
.LBB0_718:
	v_ashrrev_i64 v[10:11], 6, v[6:7]
	v_ashrrev_i32_e32 v0, 31, v7
	v_mov_b64_e32 v[2:3], s[84:85]
	v_lshrrev_b32_e32 v0, 20, v0
	v_mad_u64_u32 v[2:3], s[28:29], v10, s31, v[2:3]
	v_lshl_add_u64 v[12:13], v[10:11], 0, v[0:1]
	v_mov_b32_e32 v0, v3
	v_and_b32_e32 v14, 0x1f8, v8
	v_mad_u64_u32 v[4:5], s[28:29], v11, s31, v[0:1]
	v_mov_b32_e32 v3, v4
	v_lshlrev_b32_e32 v0, 1, v14
	v_lshl_add_u64 v[20:21], v[2:3], 0, v[0:1]
	global_load_dwordx4 v[2:5], v[20:21], off
	v_and_b32_e32 v12, 0xfffff000, v12
	v_sub_co_u32_e32 v22, vcc, v10, v12
	v_lshlrev_b32_e32 v12, 2, v14
	s_nop 0
	v_subb_co_u32_e32 v23, vcc, v11, v13, vcc
	v_mov_b32_e32 v13, v1
	v_mov_b32_e32 v26, 0
	v_lshl_add_u64 v[18:19], s[0:1], 0, v[12:13]
	v_add_co_u32_e32 v160, vcc, 0xffffe000, v20
	s_nop 1
	v_addc_co_u32_e32 v161, vcc, -1, v21, vcc
	v_add_co_u32_e32 v162, vcc, 0xfffff000, v20
	s_nop 1
	v_addc_co_u32_e32 v163, vcc, -1, v21, vcc
	v_add_co_u32_e32 v164, vcc, 0x1000, v18
	s_nop 1
	v_addc_co_u32_e32 v165, vcc, 0, v19, vcc
	global_load_dwordx4 v[100:103], v[160:161], off
	global_load_dwordx4 v[104:107], v[162:163], off offset:-3072
	global_load_dwordx4 v[108:111], v[18:19], off offset:16
	global_load_dwordx4 v[112:115], v[18:19], off
	global_load_dwordx4 v[116:119], v[20:21], off offset:-3584
	global_load_dwordx4 v[120:123], v[20:21], off offset:-2560
	global_load_dwordx4 v[124:127], v[18:19], off offset:2064
	global_load_dwordx4 v[136:139], v[18:19], off offset:2048
	global_load_dwordx4 v[140:143], v[20:21], off offset:1024
	global_load_dwordx4 v[144:147], v[20:21], off offset:2048
	global_load_dwordx4 v[148:151], v[164:165], off
	global_load_dwordx4 v[152:155], v[164:165], off offset:16
	v_cmp_lt_i64_e32 vcc, 1, v[22:23]
	v_mov_b32_e32 v27, 0
	v_mov_b32_e32 v12, 0
	v_mov_b32_e32 v13, 0
	v_mov_b32_e32 v14, 0
	v_mov_b32_e32 v15, v26
	v_mov_b32_e32 v16, v26
	v_mov_b32_e32 v17, v26
	v_mov_b32_e32 v24, 0
	v_mov_b32_e32 v25, 0
	s_and_saveexec_b64 s[28:29], vcc
	s_cbranch_execnz .LBB0_721
	s_or_b64 exec, exec, s[28:29]
	v_cmp_lt_i64_e32 vcc, 0, v[22:23]
	s_and_saveexec_b64 s[28:29], vcc
	s_cbranch_execnz .LBB0_722

.LBB0_721:
	v_add_co_u32_e32 v12, vcc, 0xffffe000, v20
	s_nop 1
	v_addc_co_u32_e32 v13, vcc, -1, v21, vcc
	v_add_co_u32_e32 v12, vcc, 0xfffff000, v20
	s_waitcnt vmcnt(0)
	v_mov_b32_e32 v24, v100
	v_mov_b32_e32 v25, v101
	v_mov_b32_e32 v26, v102
	v_mov_b32_e32 v27, v103
	v_lshlrev_b32_e32 v16, 16, v24
	v_addc_co_u32_e32 v13, vcc, -1, v21, vcc
	s_nop 0
	v_and_b32_e32 v17, 0xffff0000, v24
	s_waitcnt vmcnt(0)
	v_mov_b32_e32 v28, v104
	v_mov_b32_e32 v29, v105
	v_mov_b32_e32 v30, v106
	v_mov_b32_e32 v31, v107
	v_mov_b32_e32 v32, v108
	v_mov_b32_e32 v33, v109
	v_mov_b32_e32 v34, v110
	v_mov_b32_e32 v35, v111
	v_mov_b32_e32 v12, v112
	v_mov_b32_e32 v13, v113
	v_mov_b32_e32 v14, v114
	v_mov_b32_e32 v15, v115
	v_lshlrev_b32_e32 v24, 16, v30
	s_waitcnt vmcnt(0)
	v_pk_mul_f32 v[12:13], v[12:13], v[16:17]
	v_lshlrev_b32_e32 v16, 16, v28
	v_and_b32_e32 v17, 0xffff0000, v28
	v_pk_fma_f32 v[12:13], v[12:13], v[16:17], 0 op_sel_hi:[1,1,0]
	v_lshlrev_b32_e32 v16, 16, v25
	v_and_b32_e32 v17, 0xffff0000, v25
	v_pk_mul_f32 v[14:15], v[14:15], v[16:17]
	v_lshlrev_b32_e32 v16, 16, v29
	v_and_b32_e32 v17, 0xffff0000, v29
	v_pk_fma_f32 v[14:15], v[14:15], v[16:17], 0 op_sel_hi:[1,1,0]
	v_lshlrev_b32_e32 v16, 16, v26
	v_and_b32_e32 v17, 0xffff0000, v26
	v_pk_mul_f32 v[16:17], v[32:33], v[16:17]
	v_and_b32_e32 v25, 0xffff0000, v30
	v_pk_fma_f32 v[16:17], v[16:17], v[24:25], 0 op_sel_hi:[1,1,0]
	v_lshlrev_b32_e32 v24, 16, v27
	v_and_b32_e32 v25, 0xffff0000, v27
	v_pk_mul_f32 v[24:25], v[34:35], v[24:25]
	v_lshlrev_b32_e32 v26, 16, v31
	v_and_b32_e32 v27, 0xffff0000, v31
	v_pk_fma_f32 v[26:27], v[24:25], v[26:27], 0 op_sel_hi:[1,1,0]
	s_nop 0
	v_mov_b32_e32 v24, v26
	v_mov_b32_e32 v25, v27
	s_or_b64 exec, exec, s[28:29]
	v_cmp_lt_i64_e32 vcc, 0, v[22:23]
	s_and_saveexec_b64 s[28:29], vcc
	s_cbranch_execz .LBB0_720
.LBB0_722:
	s_waitcnt vmcnt(0)
	v_mov_b32_e32 v28, v116
	v_mov_b32_e32 v29, v117
	v_mov_b32_e32 v30, v118
	v_mov_b32_e32 v31, v119
	v_mov_b32_e32 v32, v120
	v_mov_b32_e32 v33, v121
	v_mov_b32_e32 v34, v122
	v_mov_b32_e32 v35, v123
	v_mov_b32_e32 v36, v124
	v_mov_b32_e32 v37, v125
	v_mov_b32_e32 v38, v126
	v_mov_b32_e32 v39, v127
	v_mov_b32_e32 v40, v136
	v_mov_b32_e32 v41, v137
	v_mov_b32_e32 v42, v138
	v_mov_b32_e32 v43, v139
	v_lshlrev_b32_e32 v24, 16, v28
	v_and_b32_e32 v25, 0xffff0000, v28
	s_waitcnt vmcnt(2)
	v_lshlrev_b32_e32 v28, 16, v33
	s_waitcnt vmcnt(0)
	v_pk_mul_f32 v[24:25], v[40:41], v[24:25]
	v_lshlrev_b32_e32 v40, 16, v32
	v_and_b32_e32 v41, 0xffff0000, v32
	v_pk_fma_f32 v[12:13], v[24:25], v[40:41], v[12:13]
	v_lshlrev_b32_e32 v24, 16, v29
	v_and_b32_e32 v25, 0xffff0000, v29
	v_pk_mul_f32 v[24:25], v[42:43], v[24:25]
	v_and_b32_e32 v29, 0xffff0000, v33
	v_pk_fma_f32 v[14:15], v[24:25], v[28:29], v[14:15]
	v_lshlrev_b32_e32 v24, 16, v30
	v_and_b32_e32 v25, 0xffff0000, v30
	v_pk_mul_f32 v[24:25], v[36:37], v[24:25]
	v_lshlrev_b32_e32 v28, 16, v34
	v_and_b32_e32 v29, 0xffff0000, v34
	v_pk_fma_f32 v[16:17], v[24:25], v[28:29], v[16:17]
	v_lshlrev_b32_e32 v24, 16, v31
	v_and_b32_e32 v25, 0xffff0000, v31
	v_pk_mul_f32 v[24:25], v[38:39], v[24:25]
	v_lshlrev_b32_e32 v28, 16, v35
	v_and_b32_e32 v29, 0xffff0000, v35
	v_pk_fma_f32 v[24:25], v[24:25], v[28:29], v[26:27]
	s_or_b64 exec, exec, s[28:29]
	v_cmp_lt_i64_e32 vcc, -1, v[22:23]
	s_and_saveexec_b64 s[28:29], vcc
	s_cbranch_execz .LBB0_717
.LBB0_723:
	s_mov_b64 s[40:41], 0x1000
	v_lshl_add_u64 v[34:35], v[18:19], 0, s[40:41]
	v_add_co_u32_e32 v18, vcc, 0x1000, v18
	s_nop 0
	v_addc_co_u32_e32 v19, vcc, 0, v19, vcc
	s_nop 0
	s_waitcnt vmcnt(0)
	v_mov_b32_e32 v26, v140
	v_mov_b32_e32 v27, v141
	v_mov_b32_e32 v28, v142
	v_mov_b32_e32 v29, v143
	v_mov_b32_e32 v20, v144
	v_mov_b32_e32 v21, v145
	v_mov_b32_e32 v22, v146
	v_mov_b32_e32 v23, v147
	v_mov_b32_e32 v30, v148
	v_mov_b32_e32 v31, v149
	v_mov_b32_e32 v32, v150
	v_mov_b32_e32 v33, v151
	v_mov_b32_e32 v34, v152
	v_mov_b32_e32 v35, v153
	v_mov_b32_e32 v36, v154
	v_mov_b32_e32 v37, v155
	v_lshlrev_b32_e32 v18, 16, v26
	v_and_b32_e32 v19, 0xffff0000, v26
	s_waitcnt vmcnt(1)
	v_pk_mul_f32 v[18:19], v[30:31], v[18:19]
	v_lshlrev_b32_e32 v30, 16, v20
	v_and_b32_e32 v31, 0xffff0000, v20
	v_pk_fma_f32 v[12:13], v[18:19], v[30:31], v[12:13]
	v_lshlrev_b32_e32 v18, 16, v27
	v_and_b32_e32 v19, 0xffff0000, v27
	v_pk_mul_f32 v[18:19], v[32:33], v[18:19]
	v_lshlrev_b32_e32 v20, 16, v21
	v_and_b32_e32 v21, 0xffff0000, v21
	v_pk_fma_f32 v[14:15], v[18:19], v[20:21], v[14:15]
	v_lshlrev_b32_e32 v18, 16, v28
	v_and_b32_e32 v19, 0xffff0000, v28
	s_waitcnt vmcnt(0)
	v_pk_mul_f32 v[18:19], v[34:35], v[18:19]
	v_lshlrev_b32_e32 v20, 16, v22
	v_and_b32_e32 v21, 0xffff0000, v22
	v_pk_fma_f32 v[16:17], v[18:19], v[20:21], v[16:17]
	v_lshlrev_b32_e32 v18, 16, v29
	v_and_b32_e32 v19, 0xffff0000, v29
	v_pk_mul_f32 v[18:19], v[36:37], v[18:19]
	v_lshlrev_b32_e32 v20, 16, v23
	v_and_b32_e32 v21, 0xffff0000, v23
	v_pk_fma_f32 v[24:25], v[18:19], v[20:21], v[24:25]
	s_branch .LBB0_717
